# low-rank GEMM: each 256-col unit runs only its nonzero 128-wide K slice of the block-diagonal weights (1 of 3 K-loop trips); bit-identical
# speedup vs baseline: 1.0801x; 1.0801x over previous
.LBB0_771:
	s_andn2_b64 vcc, exec, s[2:3]
	s_cbranch_vccnz .LBB0_1028
	v_ashrrev_i32_e32 v2, 31, v0
	v_lshrrev_b32_e32 v2, 26, v2
	v_lshlrev_b32_e32 v1, 4, v0
	v_add_u32_e32 v2, v0, v2
	v_bfe_i32 v0, v0, 27, 1
	v_lshrrev_b32_e32 v0, 22, v0
	v_add_u32_e32 v0, v1, v0
	v_and_b32_e32 v0, 0xfffffc00, v0
	v_sub_u32_e32 v0, v1, v0
	s_waitcnt vmcnt(0)
	v_ashrrev_i32_e32 v8, 6, v2
	v_lshrrev_b32_e32 v2, 4, v0
	v_bitop3_b32 v0, v2, v0, 32 bitop3:0x6c
	v_ashrrev_i32_e32 v3, 31, v0
	v_lshrrev_b32_e32 v3, 26, v3
	v_lshlrev_b32_e32 v2, 3, v8
	v_add_u32_e32 v3, v0, v3
	v_and_b32_e32 v2, -16, v2
	v_ashrrev_i32_e32 v10, 6, v3
	v_and_b32_e32 v3, 0xc0, v3
	v_add_u32_e32 v2, v10, v2
	v_lshlrev_b32_e32 v4, 5, v8
	v_sub_u32_e32 v0, v0, v3
	v_and_b32_e32 v9, 32, v4
	v_ashrrev_i16_sdwa v0, v250, sext(v0) dst_sel:DWORD dst_unused:UNUSED_PAD src0_sel:DWORD src1_sel:BYTE_0
	v_lshlrev_b32_e32 v3, 1, v2
	v_lshrrev_b32_e32 v4, 2, v2
	v_and_b32_e32 v5, 3, v10
	s_mov_b32 s3, 0x1ffffe0
	v_bfe_i32 v11, v0, 0, 16
	v_and_b32_e32 v3, 24, v3
	v_and_b32_e32 v4, 4, v4
	v_and_or_b32 v5, v2, s3, v5
	s_movk_i32 s2, 0x180
	v_add_u32_e32 v0, v9, v11
	v_or3_b32 v3, v5, v4, v3
	v_mul_lo_u32 v2, v2, s2
	v_add_lshl_u32 v48, v0, v2, 1
	v_mul_lo_u32 v2, v3, s2
	v_add_lshl_u32 v50, v2, v0, 1
	v_add_u32_e32 v0, 0x2000, v1
	v_ashrrev_i32_e32 v1, 31, v0
	v_lshrrev_b32_e32 v1, 22, v1
	v_add_u32_e32 v1, v0, v1
	v_ashrrev_i32_e32 v12, 10, v1
	v_mul_i32_i24_e32 v1, 0x400, v12
	v_sub_u32_e32 v0, v0, v1
	v_lshrrev_b32_e32 v1, 4, v0
	v_bitop3_b32 v0, v1, v0, 32 bitop3:0x6c
	v_ashrrev_i32_e32 v2, 31, v0
	v_lshrrev_b32_e32 v2, 26, v2
	v_lshlrev_b32_e32 v1, 3, v12
	v_add_u32_e32 v2, v0, v2
	v_and_b32_e32 v1, -16, v1
	v_ashrrev_i32_e32 v14, 6, v2
	v_and_b32_e32 v2, 0xc0, v2
	v_add_u32_e32 v1, v14, v1
	v_lshlrev_b32_e32 v3, 5, v12
	v_sub_u32_e32 v0, v0, v2
	v_and_b32_e32 v13, 32, v3
	v_ashrrev_i16_sdwa v0, v250, sext(v0) dst_sel:DWORD dst_unused:UNUSED_PAD src0_sel:DWORD src1_sel:BYTE_0
	v_lshlrev_b32_e32 v2, 1, v1
	v_lshrrev_b32_e32 v3, 2, v1
	v_and_b32_e32 v4, 3, v14
	v_bfe_i32 v15, v0, 0, 16
	v_and_b32_e32 v2, 24, v2
	v_and_b32_e32 v3, 4, v3
	v_and_or_b32 v4, v1, s3, v4
	s_ashr_i32 s11, s10, 6
	v_add_u32_e32 v0, v13, v15
	v_or3_b32 v2, v4, v3, v2
	v_mul_lo_u32 v1, v1, s2
	s_ashr_i32 s14, s10, 8
	s_lshl_b32 s46, s11, 10
	s_mul_i32 s3, s1, 0x30000
	v_readlane_b32 s8, v253, 17
	v_add_lshl_u32 v132, v0, v1, 1
	v_mul_lo_u32 v1, v2, s2
	s_mul_hi_i32 s2, s1, 0x30000
	v_readlane_b32 s9, v253, 18
	s_add_u32 s12, s8, s3
	s_addc_u32 s13, s9, s2
	s_mul_i32 s100, s1, 0x56
	s_lshr_b32 s100, s100, 8
	s_lshl_b32 s100, s100, 8
	s_add_u32 s12, s12, s100
	s_addc_u32 s13, s13, 0
	s_add_i32 s47, s46, 0
	s_add_i32 m0, s47, 0x10000
	v_add_lshl_u32 v134, v1, v0, 1
	global_load_lds_dwordx4 v50, s[12:13]
	s_add_i32 m0, s47, 0x12000
	s_add_u32 s2, s12, 0x18000
	global_load_lds_dwordx4 v134, s[12:13]
	s_addc_u32 s3, s13, 0
	s_add_i32 m0, s47, 0x14000
	s_mul_i32 s7, s0, 0x30000
	global_load_lds_dwordx4 v50, s[2:3]
	s_add_i32 m0, s47, 0x16000
	s_mul_hi_i32 s6, s0, 0x30000
	global_load_lds_dwordx4 v134, s[2:3]
	v_readlane_b32 s2, v253, 13
	v_readlane_b32 s3, v253, 14
	s_add_u32 s2, s2, s7
	s_addc_u32 s3, s3, s6
	s_add_u32 s2, s2, s100
	s_addc_u32 s3, s3, 0
	s_add_i32 s48, s47, 0x2000
	s_mov_b32 m0, s47
	s_add_u32 s6, s2, 0x18000
	global_load_lds_dwordx4 v48, s[2:3]
	s_mov_b32 m0, s48
	s_addc_u32 s7, s3, 0
	s_add_i32 s49, s47, 0x4000
	global_load_lds_dwordx4 v132, s[2:3]
	s_mov_b32 m0, s49
	s_add_i32 s50, s47, 0x6000
	global_load_lds_dwordx4 v48, s[6:7]
	s_mov_b32 m0, s50
	v_mov_b32_e32 v135, v51
	global_load_lds_dwordx4 v132, s[6:7]
	v_mov_b32_e32 v49, v51
	v_mov_b32_e32 v133, v51
	s_cmp_eq_u32 s14, 1
	v_lshl_add_u64 v[6:7], s[12:13], 0, v[50:51]
	v_lshl_add_u64 v[4:5], s[12:13], 0, v[134:135]
	v_lshl_add_u64 v[0:1], s[2:3], 0, v[48:49]
	s_cselect_b64 s[6:7], -1, 0
	s_cmp_lg_u32 s14, 1
	v_lshl_add_u64 v[2:3], s[2:3], 0, v[132:133]
	s_cbranch_scc1 .LBB0_774
	s_barrier

.LBB0_783:
	s_nop 0
	v_cndmask_b32_e64 v0, 0, 1, s[40:41]
	v_cmp_ne_u32_e64 s[38:39], 1, v0
	s_andn2_b64 vcc, exec, s[40:41]
	s_mov_b64 s[40:41], s[2:3]
	s_cbranch_vccnz .LBB0_785
	s_mul_i32 s11, s73, 0x30000
	v_readlane_b32 s14, v253, 13
	s_mul_hi_i32 s10, s73, 0x30000
	v_readlane_b32 s15, v253, 14
	s_add_u32 s40, s14, s11
	s_addc_u32 s41, s15, s10
	s_mul_i32 s100, s72, 0x56
	s_lshr_b32 s100, s100, 8
	s_lshl_b32 s100, s100, 8
	s_add_u32 s40, s40, s100
	s_addc_u32 s41, s41, 0
.LBB0_785:
	s_and_b64 vcc, exec, s[38:39]
	s_mov_b64 s[44:45], s[12:13]
	s_cbranch_vccnz .LBB0_787
	s_mul_i32 s11, s72, 0x30000
	v_readlane_b32 s14, v253, 17
	s_mul_hi_i32 s10, s72, 0x30000
	v_readlane_b32 s15, v253, 18
	s_add_u32 s44, s14, s11
	s_addc_u32 s45, s15, s10
	s_mul_i32 s100, s72, 0x56
	s_lshr_b32 s100, s100, 8
	s_lshl_b32 s100, s100, 8
	s_add_u32 s44, s44, s100
	s_addc_u32 s45, s45, 0
.LBB0_787:
	s_add_u32 s10, s12, 0x100
	v_mov_b32_e32 v0, 0
	s_addc_u32 s11, s13, 0
	s_mov_b32 s14, 2
	v_mov_b32_e32 v1, v0
	v_mov_b32_e32 v2, v0
	v_mov_b32_e32 v3, v0
	v_mov_b32_e32 v4, v0
	v_mov_b32_e32 v5, v0
	v_mov_b32_e32 v6, v0
	v_mov_b32_e32 v7, v0
	v_mov_b32_e32 v8, v0
	v_mov_b32_e32 v9, v0
	v_mov_b32_e32 v10, v0
	v_mov_b32_e32 v11, v0
	v_mov_b32_e32 v12, v0
	v_mov_b32_e32 v13, v0
	v_mov_b32_e32 v14, v0
	v_mov_b32_e32 v15, v0
	v_mov_b32_e32 v16, v0
	v_mov_b32_e32 v17, v0
	v_mov_b32_e32 v18, v0
	v_mov_b32_e32 v19, v0
	v_mov_b32_e32 v20, v0
	v_mov_b32_e32 v21, v0
	v_mov_b32_e32 v22, v0
	v_mov_b32_e32 v23, v0
	v_mov_b32_e32 v24, v0
	v_mov_b32_e32 v25, v0
	v_mov_b32_e32 v26, v0
	v_mov_b32_e32 v27, v0
	v_mov_b32_e32 v28, v0
	v_mov_b32_e32 v29, v0
	v_mov_b32_e32 v30, v0
	v_mov_b32_e32 v31, v0
	v_mov_b32_e32 v68, v0
	v_mov_b32_e32 v69, v0
	v_mov_b32_e32 v70, v0
	v_mov_b32_e32 v71, v0
	v_mov_b32_e32 v72, v0
	v_mov_b32_e32 v73, v0
	v_mov_b32_e32 v74, v0
	v_mov_b32_e32 v75, v0
	v_mov_b32_e32 v76, v0
	v_mov_b32_e32 v77, v0
	v_mov_b32_e32 v78, v0
	v_mov_b32_e32 v79, v0
	v_mov_b32_e32 v80, v0
	v_mov_b32_e32 v81, v0
	v_mov_b32_e32 v82, v0
	v_mov_b32_e32 v83, v0
	v_mov_b32_e32 v84, v0
	v_mov_b32_e32 v85, v0
	v_mov_b32_e32 v86, v0
	v_mov_b32_e32 v87, v0
	v_mov_b32_e32 v88, v0
	v_mov_b32_e32 v89, v0
	v_mov_b32_e32 v90, v0
	v_mov_b32_e32 v91, v0
	v_mov_b32_e32 v92, v0
	v_mov_b32_e32 v93, v0
	v_mov_b32_e32 v94, v0
	v_mov_b32_e32 v95, v0
	v_mov_b32_e32 v96, v0
	v_mov_b32_e32 v97, v0
	v_mov_b32_e32 v98, v0
	v_mov_b32_e32 v99, v0
	v_mov_b32_e32 v32, v0
	v_mov_b32_e32 v33, v0
	v_mov_b32_e32 v34, v0
	v_mov_b32_e32 v35, v0
	v_mov_b32_e32 v36, v0
	v_mov_b32_e32 v37, v0
	v_mov_b32_e32 v38, v0
	v_mov_b32_e32 v39, v0
	v_mov_b32_e32 v40, v0
	v_mov_b32_e32 v41, v0
	v_mov_b32_e32 v42, v0
	v_mov_b32_e32 v43, v0
	v_mov_b32_e32 v44, v0
	v_mov_b32_e32 v45, v0
	v_mov_b32_e32 v46, v0
	v_mov_b32_e32 v47, v0
	v_mov_b32_e32 v52, v0
	v_mov_b32_e32 v53, v0
	v_mov_b32_e32 v54, v0
	v_mov_b32_e32 v55, v0
	v_mov_b32_e32 v56, v0
	v_mov_b32_e32 v57, v0
	v_mov_b32_e32 v58, v0
	v_mov_b32_e32 v59, v0
	v_mov_b32_e32 v60, v0
	v_mov_b32_e32 v61, v0
	v_mov_b32_e32 v62, v0
	v_mov_b32_e32 v63, v0
	v_mov_b32_e32 v64, v0
	v_mov_b32_e32 v65, v0
	v_mov_b32_e32 v66, v0
	v_mov_b32_e32 v67, v0
	v_mov_b32_e32 v100, v0
	v_mov_b32_e32 v101, v0
	v_mov_b32_e32 v102, v0
	v_mov_b32_e32 v103, v0
	v_mov_b32_e32 v104, v0
	v_mov_b32_e32 v105, v0
	v_mov_b32_e32 v106, v0
	v_mov_b32_e32 v107, v0
	v_mov_b32_e32 v108, v0
	v_mov_b32_e32 v109, v0
	v_mov_b32_e32 v110, v0
	v_mov_b32_e32 v111, v0
	v_mov_b32_e32 v112, v0
	v_mov_b32_e32 v113, v0
	v_mov_b32_e32 v114, v0
	v_mov_b32_e32 v115, v0
	v_mov_b32_e32 v116, v0
	v_mov_b32_e32 v117, v0
	v_mov_b32_e32 v118, v0
	v_mov_b32_e32 v119, v0
	v_mov_b32_e32 v120, v0
	v_mov_b32_e32 v121, v0
	v_mov_b32_e32 v122, v0
	v_mov_b32_e32 v123, v0
	v_mov_b32_e32 v124, v0
	v_mov_b32_e32 v125, v0
	v_mov_b32_e32 v126, v0
	v_mov_b32_e32 v127, v0
	v_mov_b32_e32 v128, v0
	v_mov_b32_e32 v129, v0
	v_mov_b32_e32 v130, v0
	v_mov_b32_e32 v131, v0

	.amdhsa_kernel _Z10fwd_kernel4Args
		.amdhsa_group_segment_fixed_size 0
		.amdhsa_private_segment_fixed_size 0
		.amdhsa_kernarg_size 480
		.amdhsa_user_sgpr_count 2
		.amdhsa_user_sgpr_dispatch_ptr 0
		.amdhsa_user_sgpr_queue_ptr 0
		.amdhsa_user_sgpr_kernarg_segment_ptr 1
		.amdhsa_user_sgpr_dispatch_id 0
		.amdhsa_user_sgpr_kernarg_preload_length 0
		.amdhsa_user_sgpr_kernarg_preload_offset 0
		.amdhsa_user_sgpr_private_segment_size 0
		.amdhsa_uses_dynamic_stack 0
		.amdhsa_enable_private_segment 0
		.amdhsa_system_sgpr_workgroup_id_x 1
		.amdhsa_system_sgpr_workgroup_id_y 0
		.amdhsa_system_sgpr_workgroup_id_z 0
		.amdhsa_system_sgpr_workgroup_info 0
		.amdhsa_system_vgpr_workitem_id 2
		.amdhsa_next_free_vgpr 256
		.amdhsa_next_free_sgpr 102
		.amdhsa_accum_offset 256
		.amdhsa_reserve_vcc 1
		.amdhsa_float_round_mode_32 0
		.amdhsa_float_round_mode_16_64 0
		.amdhsa_float_denorm_mode_32 3
		.amdhsa_float_denorm_mode_16_64 3
		.amdhsa_dx10_clamp 1
		.amdhsa_ieee_mode 1
		.amdhsa_fp16_overflow 0
		.amdhsa_tg_split 0
		.amdhsa_exception_fp_ieee_invalid_op 0
		.amdhsa_exception_fp_denorm_src 0
		.amdhsa_exception_fp_ieee_div_zero 0
		.amdhsa_exception_fp_ieee_overflow 0
		.amdhsa_exception_fp_ieee_underflow 0
		.amdhsa_exception_fp_ieee_inexact 0
		.amdhsa_exception_int_div_zero 0
	.end_amdhsa_kernel

amdhsa.kernels:
  - .agpr_count:     0
    .args:
      - .offset:         0
        .size:           224
        .value_kind:     by_value
      - .offset:         224
        .size:           4
        .value_kind:     hidden_block_count_x
      - .offset:         228
        .size:           4
        .value_kind:     hidden_block_count_y
      - .offset:         232
        .size:           4
        .value_kind:     hidden_block_count_z
      - .offset:         236
        .size:           2
        .value_kind:     hidden_group_size_x
      - .offset:         238
        .size:           2
        .value_kind:     hidden_group_size_y
      - .offset:         240
        .size:           2
        .value_kind:     hidden_group_size_z
      - .offset:         242
        .size:           2
        .value_kind:     hidden_remainder_x
      - .offset:         244
        .size:           2
        .value_kind:     hidden_remainder_y
      - .offset:         246
        .size:           2
        .value_kind:     hidden_remainder_z
      - .offset:         264
        .size:           8
        .value_kind:     hidden_global_offset_x
      - .offset:         272
        .size:           8
        .value_kind:     hidden_global_offset_y
      - .offset:         280
        .size:           8
        .value_kind:     hidden_global_offset_z
      - .offset:         288
        .size:           2
        .value_kind:     hidden_grid_dims
      - .offset:         312
        .size:           8
        .value_kind:     hidden_multigrid_sync_arg
      - .offset:         344
        .size:           4
        .value_kind:     hidden_dynamic_lds_size
    .group_segment_fixed_size: 0
    .kernarg_segment_align: 8
    .kernarg_segment_size: 480
    .language:       OpenCL C
    .language_version:
      - 2
      - 0
    .max_flat_workgroup_size: 512
    .name:           _Z10fwd_kernel4Args
    .private_segment_fixed_size: 0
    .sgpr_count:     108
    .sgpr_spill_count: 290
    .symbol:         _Z10fwd_kernel4Args.kd
    .uniform_work_group_size: 1
    .uses_dynamic_stack: false
    .vgpr_count:     256
    .vgpr_spill_count: 0
    .wavefront_size: 64
